# v12 + sample-attention QK and PV inner loops: LDS reads batched (one or two waits per dot instead of 32/66), same FMA order
# speedup vs baseline: 1.0020x; 1.0020x over previous
; __device__ __forceinline__ void attn_sample_item(const Params& P, LAS unsigned char* lds, int l, int db, int kvh, int tid_in) {
;     ...
;     for (int e = tid; e < 16 * 132; e += 512) {
;         const int row = e / 132, key = e % 132, s = row & 3;
;         float acc = 0.f;
; #pragma unroll 16
;         for (int d = 0; d < 64; ++d) acc += qs[row * 64 + d] * Ks[key * 65 + d];
;         const bool ok = key < 128 ? key > s : (key - 128) <= s;
;         S[e] = ok ? acc : -1e30f;
;     }
.LBB0_1002:
	s_mov_b32 s0, 0x3e0f83e1
	v_mul_hi_i32 v2, v1, s0
	v_lshrrev_b32_e32 v3, 31, v2
	v_ashrrev_i32_e32 v2, 5, v2
	v_add_u32_e32 v4, v2, v3
	s_movk_i32 s0, 0x84
	v_mul_lo_u32 v2, v4, s0
	v_sub_u32_e32 v2, v1, v2
	v_mul_lo_u32 v3, v2, s83
	v_add_u32_e32 v5, 0, v3
	v_lshl_add_u32 v6, v4, 8, 0
	v_mov_b32_e32 v3, 0
	v_add_u32_e32 v7, 0x10a10, v6
	ds_read_b128 v[12:15], v7 offset:0
	ds_read2_b32 v[88:89], v5 offset0:0 offset1:1
	ds_read2_b32 v[90:91], v5 offset0:2 offset1:3
	ds_read_b128 v[16:19], v7 offset:16
	ds_read2_b32 v[92:93], v5 offset0:4 offset1:5
	ds_read2_b32 v[94:95], v5 offset0:6 offset1:7
	ds_read_b128 v[20:23], v7 offset:32
	ds_read2_b32 v[96:97], v5 offset0:8 offset1:9
	ds_read2_b32 v[98:99], v5 offset0:10 offset1:11
	ds_read_b128 v[24:27], v7 offset:48
	ds_read2_b32 v[100:101], v5 offset0:12 offset1:13
	ds_read2_b32 v[102:103], v5 offset0:14 offset1:15
	ds_read_b128 v[28:31], v7 offset:64
	ds_read2_b32 v[104:105], v5 offset0:16 offset1:17
	ds_read2_b32 v[106:107], v5 offset0:18 offset1:19
	ds_read_b128 v[32:35], v7 offset:80
	ds_read2_b32 v[108:109], v5 offset0:20 offset1:21
	ds_read2_b32 v[110:111], v5 offset0:22 offset1:23
	ds_read_b128 v[36:39], v7 offset:96
	ds_read2_b32 v[112:113], v5 offset0:24 offset1:25
	ds_read2_b32 v[114:115], v5 offset0:26 offset1:27
	ds_read_b128 v[48:51], v7 offset:112
	ds_read2_b32 v[116:117], v5 offset0:28 offset1:29
	ds_read2_b32 v[118:119], v5 offset0:30 offset1:31
	ds_read_b128 v[52:55], v7 offset:128
	ds_read2_b32 v[156:157], v5 offset0:32 offset1:33
	ds_read2_b32 v[158:159], v5 offset0:34 offset1:35
	ds_read_b128 v[56:59], v7 offset:144
	ds_read2_b32 v[160:161], v5 offset0:36 offset1:37
	ds_read2_b32 v[162:163], v5 offset0:38 offset1:39
	ds_read_b128 v[60:63], v7 offset:160
	ds_read2_b32 v[164:165], v5 offset0:40 offset1:41
	ds_read2_b32 v[166:167], v5 offset0:42 offset1:43
	ds_read_b128 v[64:67], v7 offset:176
	ds_read2_b32 v[168:169], v5 offset0:44 offset1:45
	ds_read2_b32 v[170:171], v5 offset0:46 offset1:47
	ds_read_b128 v[68:71], v7 offset:192
	ds_read2_b32 v[172:173], v5 offset0:48 offset1:49
	ds_read2_b32 v[174:175], v5 offset0:50 offset1:51
	ds_read_b128 v[72:75], v7 offset:208
	ds_read2_b32 v[176:177], v5 offset0:52 offset1:53
	ds_read2_b32 v[178:179], v5 offset0:54 offset1:55
	ds_read_b128 v[76:79], v7 offset:224
	ds_read2_b32 v[180:181], v5 offset0:56 offset1:57
	ds_read2_b32 v[182:183], v5 offset0:58 offset1:59
	ds_read_b128 v[84:87], v7 offset:240
	ds_read2_b32 v[184:185], v5 offset0:60 offset1:61
	ds_read2_b32 v[186:187], v5 offset0:62 offset1:63
	s_waitcnt lgkmcnt(15)
	v_fmac_f32_e32 v3, v12, v88
	v_fmac_f32_e32 v3, v13, v89
	v_fmac_f32_e32 v3, v14, v90
	v_fmac_f32_e32 v3, v15, v91
	v_fmac_f32_e32 v3, v16, v92
	v_fmac_f32_e32 v3, v17, v93
	v_fmac_f32_e32 v3, v18, v94
	v_fmac_f32_e32 v3, v19, v95
	v_fmac_f32_e32 v3, v20, v96
	v_fmac_f32_e32 v3, v21, v97
	v_fmac_f32_e32 v3, v22, v98
	v_fmac_f32_e32 v3, v23, v99
	v_fmac_f32_e32 v3, v24, v100
	v_fmac_f32_e32 v3, v25, v101
	v_fmac_f32_e32 v3, v26, v102
	v_fmac_f32_e32 v3, v27, v103
	v_fmac_f32_e32 v3, v28, v104
	v_fmac_f32_e32 v3, v29, v105
	v_fmac_f32_e32 v3, v30, v106
	v_fmac_f32_e32 v3, v31, v107
	v_fmac_f32_e32 v3, v32, v108
	v_fmac_f32_e32 v3, v33, v109
	v_fmac_f32_e32 v3, v34, v110
	v_fmac_f32_e32 v3, v35, v111
	v_fmac_f32_e32 v3, v36, v112
	v_fmac_f32_e32 v3, v37, v113
	v_fmac_f32_e32 v3, v38, v114
	v_fmac_f32_e32 v3, v39, v115
	v_fmac_f32_e32 v3, v48, v116
	v_fmac_f32_e32 v3, v49, v117
	v_fmac_f32_e32 v3, v50, v118
	v_fmac_f32_e32 v3, v51, v119
	v_fmac_f32_e32 v3, v52, v156
	v_fmac_f32_e32 v3, v53, v157
	v_fmac_f32_e32 v3, v54, v158
	v_fmac_f32_e32 v3, v55, v159
	v_fmac_f32_e32 v3, v56, v160
	v_fmac_f32_e32 v3, v57, v161
	v_fmac_f32_e32 v3, v58, v162
	v_fmac_f32_e32 v3, v59, v163
	v_fmac_f32_e32 v3, v60, v164
	v_fmac_f32_e32 v3, v61, v165
	v_fmac_f32_e32 v3, v62, v166
	v_fmac_f32_e32 v3, v63, v167
	s_waitcnt lgkmcnt(0)
	v_fmac_f32_e32 v3, v64, v168
	v_fmac_f32_e32 v3, v65, v169
	v_fmac_f32_e32 v3, v66, v170
	v_fmac_f32_e32 v3, v67, v171
	v_fmac_f32_e32 v3, v68, v172
	v_fmac_f32_e32 v3, v69, v173
	v_fmac_f32_e32 v3, v70, v174
	v_fmac_f32_e32 v3, v71, v175
	v_fmac_f32_e32 v3, v72, v176
	v_fmac_f32_e32 v3, v73, v177
	v_fmac_f32_e32 v3, v74, v178
	v_fmac_f32_e32 v3, v75, v179
	v_fmac_f32_e32 v3, v76, v180
	v_fmac_f32_e32 v3, v77, v181
	v_fmac_f32_e32 v3, v78, v182
	v_fmac_f32_e32 v3, v79, v183
	v_fmac_f32_e32 v3, v84, v184
	v_fmac_f32_e32 v3, v85, v185
	v_fmac_f32_e32 v3, v86, v186
	v_fmac_f32_e32 v3, v87, v187
	v_and_b32_e32 v4, 3, v4
	v_add_u32_e32 v5, 0xffffff80, v2
	v_cmp_le_i32_e32 vcc, v5, v4
	s_movk_i32 s0, 0x80
	s_nop 0
	v_cndmask_b32_e64 v5, 0, 1, vcc
	v_cmp_gt_i32_e32 vcc, v2, v4
	s_nop 1
	v_cndmask_b32_e64 v4, 0, 1, vcc
	v_cmp_gt_i32_e32 vcc, s0, v2
	s_movk_i32 s0, 0x63f
	s_nop 0
	v_cndmask_b32_e32 v2, v5, v4, vcc
	v_and_b32_e32 v2, 1, v2
	v_cmp_eq_u32_e32 vcc, 1, v2
	s_nop 1
	v_cndmask_b32_e32 v2, v233, v3, vcc
	v_lshl_add_u32 v3, v1, 2, 0
	v_add_u32_e32 v3, 0x11a10, v3
	ds_write_b32 v3, v2
	v_add_u32_e32 v2, 0x200, v1
	v_cmp_lt_i32_e32 vcc, s0, v1
	s_or_b64 s[4:5], vcc, s[4:5]
	v_mov_b32_e32 v1, v2
	s_andn2_b64 exec, exec, s[4:5]
	s_cbranch_execnz .LBB0_1002

; __device__ __forceinline__ void attn_sample_item(const Params& P, LAS unsigned char* lds, int l, int db, int kvh, int tid_in) {
;     ...
;     for (int e = tid; e < 16 * 64; e += 512) {
;         const int row = e >> 6, d = e & 63, g = row >> 2, s = row & 3;
;         float acc = 0.f;
; #pragma unroll 4
;         for (int key = 0; key < 132; ++key) acc += S[row * 132 + key] * Vs[key * 64 + d];
.LBB0_1015:
	v_ashrrev_i32_e32 v1, 6, v8
	v_mul_lo_u32 v3, v1, s57
	v_mov_b32_e32 v1, 0
	v_add_u32_e32 v5, 0x11a10, v3
	ds_read_b128 v[12:15], v5 offset:0
	ds_read2st64_b32 v[88:89], v2 offset0:0 offset1:1
	ds_read2st64_b32 v[90:91], v2 offset0:2 offset1:3
	ds_read_b128 v[16:19], v5 offset:16
	ds_read2st64_b32 v[92:93], v2 offset0:4 offset1:5
	ds_read2st64_b32 v[94:95], v2 offset0:6 offset1:7
	ds_read_b128 v[20:23], v5 offset:32
	ds_read2st64_b32 v[96:97], v2 offset0:8 offset1:9
	ds_read2st64_b32 v[98:99], v2 offset0:10 offset1:11
	ds_read_b128 v[24:27], v5 offset:48
	ds_read2st64_b32 v[100:101], v2 offset0:12 offset1:13
	ds_read2st64_b32 v[102:103], v2 offset0:14 offset1:15
	ds_read_b128 v[28:31], v5 offset:64
	ds_read2st64_b32 v[104:105], v2 offset0:16 offset1:17
	ds_read2st64_b32 v[106:107], v2 offset0:18 offset1:19
	ds_read_b128 v[32:35], v5 offset:80
	ds_read2st64_b32 v[108:109], v2 offset0:20 offset1:21
	ds_read2st64_b32 v[110:111], v2 offset0:22 offset1:23
	ds_read_b128 v[36:39], v5 offset:96
	ds_read2st64_b32 v[112:113], v2 offset0:24 offset1:25
	ds_read2st64_b32 v[114:115], v2 offset0:26 offset1:27
	ds_read_b128 v[48:51], v5 offset:112
	ds_read2st64_b32 v[116:117], v2 offset0:28 offset1:29
	ds_read2st64_b32 v[118:119], v2 offset0:30 offset1:31
	s_waitcnt lgkmcnt(0)
	v_fmac_f32_e32 v1, v12, v88
	v_fmac_f32_e32 v1, v13, v89
	v_fmac_f32_e32 v1, v14, v90
	v_fmac_f32_e32 v1, v15, v91
	v_fmac_f32_e32 v1, v16, v92
	v_fmac_f32_e32 v1, v17, v93
	v_fmac_f32_e32 v1, v18, v94
	v_fmac_f32_e32 v1, v19, v95
	v_fmac_f32_e32 v1, v20, v96
	v_fmac_f32_e32 v1, v21, v97
	v_fmac_f32_e32 v1, v22, v98
	v_fmac_f32_e32 v1, v23, v99
	v_fmac_f32_e32 v1, v24, v100
	v_fmac_f32_e32 v1, v25, v101
	v_fmac_f32_e32 v1, v26, v102
	v_fmac_f32_e32 v1, v27, v103
	v_fmac_f32_e32 v1, v28, v104
	v_fmac_f32_e32 v1, v29, v105
	v_fmac_f32_e32 v1, v30, v106
	v_fmac_f32_e32 v1, v31, v107
	v_fmac_f32_e32 v1, v32, v108
	v_fmac_f32_e32 v1, v33, v109
	v_fmac_f32_e32 v1, v34, v110
	v_fmac_f32_e32 v1, v35, v111
	v_fmac_f32_e32 v1, v36, v112
	v_fmac_f32_e32 v1, v37, v113
	v_fmac_f32_e32 v1, v38, v114
	v_fmac_f32_e32 v1, v39, v115
	v_fmac_f32_e32 v1, v48, v116
	v_fmac_f32_e32 v1, v49, v117
	v_fmac_f32_e32 v1, v50, v118
	v_fmac_f32_e32 v1, v51, v119
	ds_read_b128 v[12:15], v5 offset:128
	ds_read2st64_b32 v[88:89], v2 offset0:32 offset1:33
	ds_read2st64_b32 v[90:91], v2 offset0:34 offset1:35
	ds_read_b128 v[16:19], v5 offset:144
	ds_read2st64_b32 v[92:93], v2 offset0:36 offset1:37
	ds_read2st64_b32 v[94:95], v2 offset0:38 offset1:39
	ds_read_b128 v[20:23], v5 offset:160
	ds_read2st64_b32 v[96:97], v2 offset0:40 offset1:41
	ds_read2st64_b32 v[98:99], v2 offset0:42 offset1:43
	ds_read_b128 v[24:27], v5 offset:176
	ds_read2st64_b32 v[100:101], v2 offset0:44 offset1:45
	ds_read2st64_b32 v[102:103], v2 offset0:46 offset1:47
	ds_read_b128 v[28:31], v5 offset:192
	ds_read2st64_b32 v[104:105], v2 offset0:48 offset1:49
	ds_read2st64_b32 v[106:107], v2 offset0:50 offset1:51
	ds_read_b128 v[32:35], v5 offset:208
	ds_read2st64_b32 v[108:109], v2 offset0:52 offset1:53
	ds_read2st64_b32 v[110:111], v2 offset0:54 offset1:55
	ds_read_b128 v[36:39], v5 offset:224
	ds_read2st64_b32 v[112:113], v2 offset0:56 offset1:57
	ds_read2st64_b32 v[114:115], v2 offset0:58 offset1:59
	ds_read_b128 v[48:51], v5 offset:240
	ds_read2st64_b32 v[116:117], v2 offset0:60 offset1:61
	ds_read2st64_b32 v[118:119], v2 offset0:62 offset1:63
	s_waitcnt lgkmcnt(0)
	v_fmac_f32_e32 v1, v12, v88
	v_fmac_f32_e32 v1, v13, v89
	v_fmac_f32_e32 v1, v14, v90
	v_fmac_f32_e32 v1, v15, v91
	v_fmac_f32_e32 v1, v16, v92
	v_fmac_f32_e32 v1, v17, v93
	v_fmac_f32_e32 v1, v18, v94
	v_fmac_f32_e32 v1, v19, v95
	v_fmac_f32_e32 v1, v20, v96
	v_fmac_f32_e32 v1, v21, v97
	v_fmac_f32_e32 v1, v22, v98
	v_fmac_f32_e32 v1, v23, v99
	v_fmac_f32_e32 v1, v24, v100
	v_fmac_f32_e32 v1, v25, v101
	v_fmac_f32_e32 v1, v26, v102
	v_fmac_f32_e32 v1, v27, v103
	v_fmac_f32_e32 v1, v28, v104
	v_fmac_f32_e32 v1, v29, v105
	v_fmac_f32_e32 v1, v30, v106
	v_fmac_f32_e32 v1, v31, v107
	v_fmac_f32_e32 v1, v32, v108
	v_fmac_f32_e32 v1, v33, v109
	v_fmac_f32_e32 v1, v34, v110
	v_fmac_f32_e32 v1, v35, v111
	v_fmac_f32_e32 v1, v36, v112
	v_fmac_f32_e32 v1, v37, v113
	v_fmac_f32_e32 v1, v38, v114
	v_fmac_f32_e32 v1, v39, v115
	v_fmac_f32_e32 v1, v48, v116
	v_fmac_f32_e32 v1, v49, v117
	v_fmac_f32_e32 v1, v50, v118
	v_fmac_f32_e32 v1, v51, v119
	ds_read_b128 v[12:15], v5 offset:256
	ds_read2st64_b32 v[88:89], v2 offset0:64 offset1:65
	ds_read2st64_b32 v[90:91], v2 offset0:66 offset1:67
	ds_read_b128 v[16:19], v5 offset:272
	ds_read2st64_b32 v[92:93], v2 offset0:68 offset1:69
	ds_read2st64_b32 v[94:95], v2 offset0:70 offset1:71
	ds_read_b128 v[20:23], v5 offset:288
	ds_read2st64_b32 v[96:97], v2 offset0:72 offset1:73
	ds_read2st64_b32 v[98:99], v2 offset0:74 offset1:75
	ds_read_b128 v[24:27], v5 offset:304
	ds_read2st64_b32 v[100:101], v2 offset0:76 offset1:77
	ds_read2st64_b32 v[102:103], v2 offset0:78 offset1:79
	ds_read_b128 v[28:31], v5 offset:320
	ds_read2st64_b32 v[104:105], v2 offset0:80 offset1:81
	ds_read2st64_b32 v[106:107], v2 offset0:82 offset1:83
	ds_read_b128 v[32:35], v5 offset:336
	ds_read2st64_b32 v[108:109], v2 offset0:84 offset1:85
	ds_read2st64_b32 v[110:111], v2 offset0:86 offset1:87
	ds_read_b128 v[36:39], v5 offset:352
	ds_read2st64_b32 v[112:113], v2 offset0:88 offset1:89
	ds_read2st64_b32 v[114:115], v2 offset0:90 offset1:91
	ds_read_b128 v[48:51], v5 offset:368
	ds_read2st64_b32 v[116:117], v2 offset0:92 offset1:93
	ds_read2st64_b32 v[118:119], v2 offset0:94 offset1:95
	s_waitcnt lgkmcnt(0)
; __device__ __forceinline__ bf16 f2bf(float f) { return (bf16)(cvtpk(f, 0.f) & 0xffffu); }
; __device__ __forceinline__ void attn_sample_item(const Params& P, LAS unsigned char* lds, int l, int db, int kvh, int tid_in) {
;     ...
;     for (int e = tid; e < 16 * 64; e += 512) {
;         const int row = e >> 6, d = e & 63, g = row >> 2, s = row & 3;
;         float acc = 0.f;
; #pragma unroll 4
;         for (int key = 0; key < 132; ++key) acc += S[row * 132 + key] * Vs[key * 64 + d];
;         ATT[(size_t)(NPT + db * 4 + s) * 512 + (kvh * 4 + g) * 64 + d] = f2bf(acc);
;     }
	v_fmac_f32_e32 v1, v12, v88
	v_fmac_f32_e32 v1, v13, v89
	v_fmac_f32_e32 v1, v14, v90
	v_fmac_f32_e32 v1, v15, v91
	v_fmac_f32_e32 v1, v16, v92
	v_fmac_f32_e32 v1, v17, v93
	v_fmac_f32_e32 v1, v18, v94
	v_fmac_f32_e32 v1, v19, v95
	v_fmac_f32_e32 v1, v20, v96
	v_fmac_f32_e32 v1, v21, v97
	v_fmac_f32_e32 v1, v22, v98
	v_fmac_f32_e32 v1, v23, v99
	v_fmac_f32_e32 v1, v24, v100
	v_fmac_f32_e32 v1, v25, v101
	v_fmac_f32_e32 v1, v26, v102
	v_fmac_f32_e32 v1, v27, v103
	v_fmac_f32_e32 v1, v28, v104
	v_fmac_f32_e32 v1, v29, v105
	v_fmac_f32_e32 v1, v30, v106
	v_fmac_f32_e32 v1, v31, v107
	v_fmac_f32_e32 v1, v32, v108
	v_fmac_f32_e32 v1, v33, v109
	v_fmac_f32_e32 v1, v34, v110
	v_fmac_f32_e32 v1, v35, v111
	v_fmac_f32_e32 v1, v36, v112
	v_fmac_f32_e32 v1, v37, v113
	v_fmac_f32_e32 v1, v38, v114
	v_fmac_f32_e32 v1, v39, v115
	v_fmac_f32_e32 v1, v48, v116
	v_fmac_f32_e32 v1, v49, v117
	v_fmac_f32_e32 v1, v50, v118
	v_fmac_f32_e32 v1, v51, v119
	ds_read_b128 v[12:15], v5 offset:384
	ds_read2st64_b32 v[88:89], v2 offset0:96 offset1:97
	ds_read2st64_b32 v[90:91], v2 offset0:98 offset1:99
	ds_read_b128 v[16:19], v5 offset:400
	ds_read2st64_b32 v[92:93], v2 offset0:100 offset1:101
	ds_read2st64_b32 v[94:95], v2 offset0:102 offset1:103
	ds_read_b128 v[20:23], v5 offset:416
	ds_read2st64_b32 v[96:97], v2 offset0:104 offset1:105
	ds_read2st64_b32 v[98:99], v2 offset0:106 offset1:107
	ds_read_b128 v[24:27], v5 offset:432
	ds_read2st64_b32 v[100:101], v2 offset0:108 offset1:109
	ds_read2st64_b32 v[102:103], v2 offset0:110 offset1:111
	ds_read_b128 v[28:31], v5 offset:448
	ds_read2st64_b32 v[104:105], v2 offset0:112 offset1:113
	ds_read2st64_b32 v[106:107], v2 offset0:114 offset1:115
	ds_read_b128 v[32:35], v5 offset:464
	ds_read2st64_b32 v[108:109], v2 offset0:116 offset1:117
	ds_read2st64_b32 v[110:111], v2 offset0:118 offset1:119
	ds_read_b128 v[36:39], v5 offset:480
	ds_read2st64_b32 v[112:113], v2 offset0:120 offset1:121
	ds_read2st64_b32 v[114:115], v2 offset0:122 offset1:123
	ds_read_b128 v[48:51], v5 offset:496
	ds_read2st64_b32 v[116:117], v2 offset0:124 offset1:125
	ds_read2st64_b32 v[118:119], v2 offset0:126 offset1:127
	s_waitcnt lgkmcnt(0)
	v_fmac_f32_e32 v1, v12, v88
	v_fmac_f32_e32 v1, v13, v89
	v_fmac_f32_e32 v1, v14, v90
	v_fmac_f32_e32 v1, v15, v91
	v_fmac_f32_e32 v1, v16, v92
	v_fmac_f32_e32 v1, v17, v93
	v_fmac_f32_e32 v1, v18, v94
	v_fmac_f32_e32 v1, v19, v95
	v_fmac_f32_e32 v1, v20, v96
	v_fmac_f32_e32 v1, v21, v97
	v_fmac_f32_e32 v1, v22, v98
	v_fmac_f32_e32 v1, v23, v99
	v_fmac_f32_e32 v1, v24, v100
	v_fmac_f32_e32 v1, v25, v101
	v_fmac_f32_e32 v1, v26, v102
	v_fmac_f32_e32 v1, v27, v103
	v_fmac_f32_e32 v1, v28, v104
	v_fmac_f32_e32 v1, v29, v105
	v_fmac_f32_e32 v1, v30, v106
	v_fmac_f32_e32 v1, v31, v107
	v_fmac_f32_e32 v1, v32, v108
	v_fmac_f32_e32 v1, v33, v109
	v_fmac_f32_e32 v1, v34, v110
	v_fmac_f32_e32 v1, v35, v111
	v_fmac_f32_e32 v1, v36, v112
	v_fmac_f32_e32 v1, v37, v113
	v_fmac_f32_e32 v1, v38, v114
	v_fmac_f32_e32 v1, v39, v115
	v_fmac_f32_e32 v1, v48, v116
	v_fmac_f32_e32 v1, v49, v117
	v_fmac_f32_e32 v1, v50, v118
	v_fmac_f32_e32 v1, v51, v119
	ds_read_b128 v[12:15], v5 offset:512
	ds_read2st64_b32 v[88:89], v2 offset0:128 offset1:129
	ds_read2st64_b32 v[90:91], v2 offset0:130 offset1:131
	s_waitcnt lgkmcnt(0)
	v_fmac_f32_e32 v1, v12, v88
	v_fmac_f32_e32 v1, v13, v89
	v_fmac_f32_e32 v1, v14, v90
	v_fmac_f32_e32 v1, v15, v91
	v_lshrrev_b32_e32 v3, 6, v8
	v_cvt_pk_bf16_f32 v9, v1, s0
	v_and_or_b32 v1, v3, 3, s0
	v_lshlrev_b32_e32 v80, 9, v1
	v_ashrrev_i32_e32 v1, 2, v8
	v_and_b32_e32 v1, 0xffffffc0, v1
	v_add_u32_e32 v4, s1, v1
	v_ashrrev_i32_e32 v5, 31, v4
	v_lshl_add_u64 v[6:7], v[80:81], 1, s[86:87]
	v_lshl_add_u64 v[4:5], v[4:5], 1, v[6:7]
	v_mov_b32_e32 v1, v81
	v_lshl_add_u64 v[4:5], v[4:5], 0, v[0:1]
	v_add_u32_e32 v1, 0x200, v8
	v_cmp_lt_i32_e32 vcc, s56, v8
	s_or_b64 s[4:5], vcc, s[4:5]
	v_mov_b32_e32 v8, v1
	global_store_short v[4:5], v9, off
	s_andn2_b64 exec, exec, s[4:5]
	s_cbranch_execnz .LBB0_1015
